# skinny 128-row GEMM remainders of the N=1024 and N=2048 phases: a unit's eight wave jobs are spread over 4 / 2 workgroups (two / four waves each) instead of one workgroup doing all eight while the oth
# speedup vs baseline: 1.0189x; 1.0189x over previous
.LBB0_979:
	s_cmpk_eq_i32 s90, 0x100
	s_cbranch_scc0 .Lsks_gen_a
	s_cmp_gt_u32 s36, 1
	s_cbranch_scc1 .LBB0_984
	s_lshr_b32 s22, s2, 6
	s_mul_i32 s22, s22, 2
	s_add_i32 s22, s22, s36
	s_and_b32 s24, s2, 63
	s_movk_i32 s25, 64
	s_branch .Lsks_go_a
.Lsks_gen_a:
	s_cmp_gt_i32 s2, 63
	s_cbranch_scc1 .LBB0_984
	s_mov_b32 s22, s36
	s_mov_b32 s24, s2
	s_mov_b32 s25, s90
.Lsks_go_a:
	v_lshrrev_b32_e32 v2, 2, v146
	v_and_b32_e32 v20, 12, v2
	v_lshl_or_b32 v2, s22, 4, v1
	v_mov_b32_e32 v7, 0
	v_add_u32_e32 v6, 0x4000, v2
	v_mov_b32_e32 v3, v7
	v_lshlrev_b64 v[4:5], 12, v[2:3]
	v_lshlrev_b64 v[8:9], 12, v[6:7]
	v_and_b32_e32 v6, 48, v0
	v_lshlrev_b64 v[2:3], 11, v[2:3]
	v_or_b32_e32 v2, v2, v6
	v_lshl_add_u64 v[8:9], s[8:9], 0, v[8:9]
	s_waitcnt lgkmcnt(0)
	v_lshl_add_u64 v[10:11], s[10:11], 0, v[4:5]
	v_lshl_add_u64 v[12:13], s[30:31], 0, v[6:7]
	v_lshl_or_b32 v14, s24, 4, v1
	s_lshl_b32 s3, s25, 4
	v_lshl_add_u64 v[16:17], s[30:31], 0, v[2:3]
	s_mov_b32 s8, s24

.LBB0_982:
	v_add_co_u32_e32 v58, vcc, 0x900000, v18
	s_nop 1
	v_addc_co_u32_e32 v59, vcc, 0, v19, vcc
	v_add_co_u32_e32 v60, vcc, 0x26e13000, v16
	s_nop 1
	v_addc_co_u32_e32 v61, vcc, 0, v17, vcc
	global_load_dwordx4 v[26:29], v[58:59], off
	global_load_dwordx4 v[176:179], v[60:61], off
	global_load_dwordx4 v[30:33], v[58:59], off offset:64
	global_load_dwordx4 v[180:183], v[60:61], off offset:64
	global_load_dwordx4 v[34:37], v[58:59], off offset:128
	global_load_dwordx4 v[184:187], v[60:61], off offset:128
	global_load_dwordx4 v[38:41], v[58:59], off offset:192
	global_load_dwordx4 v[188:191], v[60:61], off offset:192
	global_load_dwordx4 v[42:45], v[58:59], off offset:256
	global_load_dwordx4 v[192:195], v[60:61], off offset:256
	global_load_dwordx4 v[46:49], v[58:59], off offset:320
	global_load_dwordx4 v[196:199], v[60:61], off offset:320
	global_load_dwordx4 v[50:53], v[58:59], off offset:384
	global_load_dwordx4 v[200:203], v[60:61], off offset:384
	global_load_dwordx4 v[54:57], v[58:59], off offset:448
	global_load_dwordx4 v[204:207], v[60:61], off offset:448
	global_load_dwordx4 v[132:135], v[58:59], off offset:512
	global_load_dwordx4 v[208:211], v[60:61], off offset:512
	global_load_dwordx4 v[136:139], v[58:59], off offset:576
	global_load_dwordx4 v[212:215], v[60:61], off offset:576
	global_load_dwordx4 v[140:143], v[58:59], off offset:640
	global_load_dwordx4 v[216:219], v[60:61], off offset:640
	global_load_dwordx4 v[148:151], v[58:59], off offset:704
	global_load_dwordx4 v[220:223], v[60:61], off offset:704
	global_load_dwordx4 v[152:155], v[58:59], off offset:768
	global_load_dwordx4 v[224:227], v[60:61], off offset:768
	global_load_dwordx4 v[156:159], v[58:59], off offset:832
	global_load_dwordx4 v[228:231], v[60:61], off offset:832
	global_load_dwordx4 v[168:171], v[58:59], off offset:896
	global_load_dwordx4 v[232:235], v[60:61], off offset:896
	global_load_dwordx4 v[172:175], v[58:59], off offset:960
	global_load_dwordx4 v[236:239], v[60:61], off offset:960
	s_waitcnt vmcnt(30)
	v_mfma_f32_16x16x32_bf16 v[2:5], v[26:29], v[176:179], v[2:5]
	global_load_dwordx4 v[26:29], v[58:59], off offset:1024
	global_load_dwordx4 v[176:179], v[60:61], off offset:1024
	s_waitcnt vmcnt(30)
	v_mfma_f32_16x16x32_bf16 v[2:5], v[30:33], v[180:183], v[2:5]
	global_load_dwordx4 v[30:33], v[58:59], off offset:1088
	global_load_dwordx4 v[180:183], v[60:61], off offset:1088
	s_waitcnt vmcnt(30)
	v_mfma_f32_16x16x32_bf16 v[2:5], v[34:37], v[184:187], v[2:5]
	global_load_dwordx4 v[34:37], v[58:59], off offset:1152
	global_load_dwordx4 v[184:187], v[60:61], off offset:1152
	s_waitcnt vmcnt(30)
	v_mfma_f32_16x16x32_bf16 v[2:5], v[38:41], v[188:191], v[2:5]
	global_load_dwordx4 v[38:41], v[58:59], off offset:1216
	global_load_dwordx4 v[188:191], v[60:61], off offset:1216
	s_waitcnt vmcnt(30)
	v_mfma_f32_16x16x32_bf16 v[2:5], v[42:45], v[192:195], v[2:5]
	global_load_dwordx4 v[42:45], v[58:59], off offset:1280
	global_load_dwordx4 v[192:195], v[60:61], off offset:1280
	s_waitcnt vmcnt(30)
	v_mfma_f32_16x16x32_bf16 v[2:5], v[46:49], v[196:199], v[2:5]
	global_load_dwordx4 v[46:49], v[58:59], off offset:1344
	global_load_dwordx4 v[196:199], v[60:61], off offset:1344
	s_waitcnt vmcnt(30)
	v_mfma_f32_16x16x32_bf16 v[2:5], v[50:53], v[200:203], v[2:5]
	global_load_dwordx4 v[50:53], v[58:59], off offset:1408
	global_load_dwordx4 v[200:203], v[60:61], off offset:1408
	s_waitcnt vmcnt(30)
	v_mfma_f32_16x16x32_bf16 v[2:5], v[54:57], v[204:207], v[2:5]
	global_load_dwordx4 v[54:57], v[58:59], off offset:1472
	global_load_dwordx4 v[204:207], v[60:61], off offset:1472
	s_waitcnt vmcnt(30)
	v_mfma_f32_16x16x32_bf16 v[2:5], v[132:135], v[208:211], v[2:5]
	global_load_dwordx4 v[132:135], v[58:59], off offset:1536
	global_load_dwordx4 v[208:211], v[60:61], off offset:1536
	s_waitcnt vmcnt(30)
	v_mfma_f32_16x16x32_bf16 v[2:5], v[136:139], v[212:215], v[2:5]
	global_load_dwordx4 v[136:139], v[58:59], off offset:1600
	global_load_dwordx4 v[212:215], v[60:61], off offset:1600
	s_waitcnt vmcnt(30)
	v_mfma_f32_16x16x32_bf16 v[2:5], v[140:143], v[216:219], v[2:5]
	global_load_dwordx4 v[140:143], v[58:59], off offset:1664
	global_load_dwordx4 v[216:219], v[60:61], off offset:1664
	s_waitcnt vmcnt(30)
	v_mfma_f32_16x16x32_bf16 v[2:5], v[148:151], v[220:223], v[2:5]
	global_load_dwordx4 v[148:151], v[58:59], off offset:1728
	global_load_dwordx4 v[220:223], v[60:61], off offset:1728
	s_waitcnt vmcnt(30)
	v_mfma_f32_16x16x32_bf16 v[2:5], v[152:155], v[224:227], v[2:5]
	global_load_dwordx4 v[152:155], v[58:59], off offset:1792
	global_load_dwordx4 v[224:227], v[60:61], off offset:1792
	s_waitcnt vmcnt(30)
	v_mfma_f32_16x16x32_bf16 v[2:5], v[156:159], v[228:231], v[2:5]
	global_load_dwordx4 v[156:159], v[58:59], off offset:1856
	global_load_dwordx4 v[228:231], v[60:61], off offset:1856
	s_waitcnt vmcnt(30)
	v_mfma_f32_16x16x32_bf16 v[2:5], v[168:171], v[232:235], v[2:5]
	global_load_dwordx4 v[168:171], v[58:59], off offset:1920
	global_load_dwordx4 v[232:235], v[60:61], off offset:1920
	s_waitcnt vmcnt(30)
	v_mfma_f32_16x16x32_bf16 v[2:5], v[172:175], v[236:239], v[2:5]
	global_load_dwordx4 v[172:175], v[58:59], off offset:1984
	global_load_dwordx4 v[236:239], v[60:61], off offset:1984
	s_waitcnt vmcnt(30)
	v_mfma_f32_16x16x32_bf16 v[2:5], v[26:29], v[176:179], v[2:5]
	s_waitcnt vmcnt(28)
	v_mfma_f32_16x16x32_bf16 v[2:5], v[30:33], v[180:183], v[2:5]
	s_waitcnt vmcnt(26)
	v_mfma_f32_16x16x32_bf16 v[2:5], v[34:37], v[184:187], v[2:5]
	s_waitcnt vmcnt(24)
	v_mfma_f32_16x16x32_bf16 v[2:5], v[38:41], v[188:191], v[2:5]
	s_waitcnt vmcnt(22)
	v_mfma_f32_16x16x32_bf16 v[2:5], v[42:45], v[192:195], v[2:5]
	s_waitcnt vmcnt(20)
	v_mfma_f32_16x16x32_bf16 v[2:5], v[46:49], v[196:199], v[2:5]
	s_waitcnt vmcnt(18)
	v_mfma_f32_16x16x32_bf16 v[2:5], v[50:53], v[200:203], v[2:5]
	s_waitcnt vmcnt(16)
	v_mfma_f32_16x16x32_bf16 v[2:5], v[54:57], v[204:207], v[2:5]
	s_waitcnt vmcnt(14)
	v_mfma_f32_16x16x32_bf16 v[2:5], v[132:135], v[208:211], v[2:5]
	s_waitcnt vmcnt(12)
	v_mfma_f32_16x16x32_bf16 v[2:5], v[136:139], v[212:215], v[2:5]
	s_waitcnt vmcnt(10)
	v_mfma_f32_16x16x32_bf16 v[2:5], v[140:143], v[216:219], v[2:5]
	s_waitcnt vmcnt(8)
	v_mfma_f32_16x16x32_bf16 v[2:5], v[148:151], v[220:223], v[2:5]
	s_waitcnt vmcnt(6)
	v_mfma_f32_16x16x32_bf16 v[2:5], v[152:155], v[224:227], v[2:5]
	s_waitcnt vmcnt(4)
	v_mfma_f32_16x16x32_bf16 v[2:5], v[156:159], v[228:231], v[2:5]
	s_waitcnt vmcnt(2)
	v_mfma_f32_16x16x32_bf16 v[2:5], v[168:171], v[232:235], v[2:5]
	s_waitcnt vmcnt(0)
	v_mfma_f32_16x16x32_bf16 v[2:5], v[172:175], v[236:239], v[2:5]
	s_movk_i32 s4, 0x800
	s_nop 1
	v_lshl_or_b32 v18, s8, 4, v20
	v_ashrrev_i32_e32 v19, 31, v18
	v_lshlrev_b64 v[18:19], 2, v[18:19]
	v_lshl_add_u64 v[22:23], v[10:11], 0, v[18:19]
	global_load_dwordx4 v[22:25], v[22:23], off
	s_add_i32 s8, s8, s25
	s_cmp_gt_i32 s8, 63
	v_lshl_add_u64 v[18:19], v[8:9], 0, v[18:19]
	v_add_u32_e32 v14, s3, v14
	s_waitcnt vmcnt(0)
	v_pk_add_f32 v[4:5], v[4:5], v[24:25]
	v_pk_add_f32 v[2:3], v[2:3], v[22:23]
	global_store_dwordx4 v[18:19], v[2:5], off
	s_cbranch_scc0 .LBB0_981

.LBB0_1107:
	s_cmpk_eq_i32 s90, 0x100
	s_cbranch_scc0 .Lsks_gen_b
	s_cmp_gt_u32 s36, 3
	s_cbranch_scc1 .LBB0_1112
	s_lshr_b32 s22, s2, 7
	s_mul_i32 s22, s22, 4
	s_add_i32 s22, s22, s36
	s_and_b32 s24, s2, 127
	s_movk_i32 s25, 128
	s_branch .Lsks_go_b
.Lsks_gen_b:
	s_cmpk_gt_i32 s2, 0x7f
	s_cbranch_scc1 .LBB0_1112
	s_mov_b32 s22, s36
	s_mov_b32 s24, s2
	s_mov_b32 s25, s90
.Lsks_go_b:
	v_lshrrev_b32_e32 v2, 2, v146
	v_and_b32_e32 v18, 12, v2
	v_lshl_or_b32 v2, s22, 4, v1
	v_mov_b32_e32 v7, 0
	v_add_u32_e32 v6, 0x4000, v2
	v_mov_b32_e32 v3, v7
	v_lshlrev_b64 v[4:5], 12, v[6:7]
	v_and_b32_e32 v6, 48, v0
	v_lshlrev_b64 v[2:3], 11, v[2:3]
	v_or_b32_e32 v2, v2, v6
	v_lshl_add_u64 v[8:9], s[8:9], 0, v[4:5]
	v_lshl_add_u64 v[10:11], s[30:31], 0, v[6:7]
	v_lshl_or_b32 v12, s24, 4, v1
	s_lshl_b32 s3, s25, 4
	v_lshl_add_u64 v[14:15], s[30:31], 0, v[2:3]
	s_mov_b32 s8, s24

.LBB0_1110:
	v_add_co_u32_e32 v56, vcc, 0x1280000, v16
	s_nop 1
	v_addc_co_u32_e32 v57, vcc, 0, v17, vcc
	v_add_co_u32_e32 v58, vcc, 0xdc51000, v14
	s_nop 1
	v_addc_co_u32_e32 v59, vcc, 0, v15, vcc
	global_load_dwordx4 v[24:27], v[56:57], off
	global_load_dwordx4 v[176:179], v[58:59], off
	global_load_dwordx4 v[28:31], v[56:57], off offset:64
	global_load_dwordx4 v[180:183], v[58:59], off offset:64
	global_load_dwordx4 v[32:35], v[56:57], off offset:128
	global_load_dwordx4 v[184:187], v[58:59], off offset:128
	global_load_dwordx4 v[36:39], v[56:57], off offset:192
	global_load_dwordx4 v[188:191], v[58:59], off offset:192
	global_load_dwordx4 v[40:43], v[56:57], off offset:256
	global_load_dwordx4 v[192:195], v[58:59], off offset:256
	global_load_dwordx4 v[44:47], v[56:57], off offset:320
	global_load_dwordx4 v[196:199], v[58:59], off offset:320
	global_load_dwordx4 v[48:51], v[56:57], off offset:384
	global_load_dwordx4 v[200:203], v[58:59], off offset:384
	global_load_dwordx4 v[52:55], v[56:57], off offset:448
	global_load_dwordx4 v[204:207], v[58:59], off offset:448
	global_load_dwordx4 v[132:135], v[56:57], off offset:512
	global_load_dwordx4 v[208:211], v[58:59], off offset:512
	global_load_dwordx4 v[136:139], v[56:57], off offset:576
	global_load_dwordx4 v[212:215], v[58:59], off offset:576
	global_load_dwordx4 v[140:143], v[56:57], off offset:640
	global_load_dwordx4 v[216:219], v[58:59], off offset:640
	global_load_dwordx4 v[148:151], v[56:57], off offset:704
	global_load_dwordx4 v[220:223], v[58:59], off offset:704
	global_load_dwordx4 v[152:155], v[56:57], off offset:768
	global_load_dwordx4 v[224:227], v[58:59], off offset:768
	global_load_dwordx4 v[156:159], v[56:57], off offset:832
	global_load_dwordx4 v[228:231], v[58:59], off offset:832
	global_load_dwordx4 v[168:171], v[56:57], off offset:896
	global_load_dwordx4 v[232:235], v[58:59], off offset:896
	global_load_dwordx4 v[172:175], v[56:57], off offset:960
	global_load_dwordx4 v[236:239], v[58:59], off offset:960
	s_waitcnt vmcnt(30)
	v_mfma_f32_16x16x32_bf16 v[2:5], v[24:27], v[176:179], v[2:5]
	global_load_dwordx4 v[24:27], v[56:57], off offset:1024
	global_load_dwordx4 v[176:179], v[58:59], off offset:1024
	s_waitcnt vmcnt(30)
	v_mfma_f32_16x16x32_bf16 v[2:5], v[28:31], v[180:183], v[2:5]
	global_load_dwordx4 v[28:31], v[56:57], off offset:1088
	global_load_dwordx4 v[180:183], v[58:59], off offset:1088
	s_waitcnt vmcnt(30)
	v_mfma_f32_16x16x32_bf16 v[2:5], v[32:35], v[184:187], v[2:5]
	global_load_dwordx4 v[32:35], v[56:57], off offset:1152
	global_load_dwordx4 v[184:187], v[58:59], off offset:1152
	s_waitcnt vmcnt(30)
	v_mfma_f32_16x16x32_bf16 v[2:5], v[36:39], v[188:191], v[2:5]
	global_load_dwordx4 v[36:39], v[56:57], off offset:1216
	global_load_dwordx4 v[188:191], v[58:59], off offset:1216
	s_waitcnt vmcnt(30)
	v_mfma_f32_16x16x32_bf16 v[2:5], v[40:43], v[192:195], v[2:5]
	global_load_dwordx4 v[40:43], v[56:57], off offset:1280
	global_load_dwordx4 v[192:195], v[58:59], off offset:1280
	s_waitcnt vmcnt(30)
	v_mfma_f32_16x16x32_bf16 v[2:5], v[44:47], v[196:199], v[2:5]
	global_load_dwordx4 v[44:47], v[56:57], off offset:1344
	global_load_dwordx4 v[196:199], v[58:59], off offset:1344
	s_waitcnt vmcnt(30)
	v_mfma_f32_16x16x32_bf16 v[2:5], v[48:51], v[200:203], v[2:5]
	global_load_dwordx4 v[48:51], v[56:57], off offset:1408
	global_load_dwordx4 v[200:203], v[58:59], off offset:1408
	s_waitcnt vmcnt(30)
	v_mfma_f32_16x16x32_bf16 v[2:5], v[52:55], v[204:207], v[2:5]
	global_load_dwordx4 v[52:55], v[56:57], off offset:1472
	global_load_dwordx4 v[204:207], v[58:59], off offset:1472
	s_waitcnt vmcnt(30)
	v_mfma_f32_16x16x32_bf16 v[2:5], v[132:135], v[208:211], v[2:5]
	global_load_dwordx4 v[132:135], v[56:57], off offset:1536
	global_load_dwordx4 v[208:211], v[58:59], off offset:1536
	s_waitcnt vmcnt(30)
	v_mfma_f32_16x16x32_bf16 v[2:5], v[136:139], v[212:215], v[2:5]
	global_load_dwordx4 v[136:139], v[56:57], off offset:1600
	global_load_dwordx4 v[212:215], v[58:59], off offset:1600
	s_waitcnt vmcnt(30)
	v_mfma_f32_16x16x32_bf16 v[2:5], v[140:143], v[216:219], v[2:5]
	global_load_dwordx4 v[140:143], v[56:57], off offset:1664
	global_load_dwordx4 v[216:219], v[58:59], off offset:1664
	s_waitcnt vmcnt(30)
	v_mfma_f32_16x16x32_bf16 v[2:5], v[148:151], v[220:223], v[2:5]
	global_load_dwordx4 v[148:151], v[56:57], off offset:1728
	global_load_dwordx4 v[220:223], v[58:59], off offset:1728
	s_waitcnt vmcnt(30)
	v_mfma_f32_16x16x32_bf16 v[2:5], v[152:155], v[224:227], v[2:5]
	global_load_dwordx4 v[152:155], v[56:57], off offset:1792
	global_load_dwordx4 v[224:227], v[58:59], off offset:1792
	s_waitcnt vmcnt(30)
	v_mfma_f32_16x16x32_bf16 v[2:5], v[156:159], v[228:231], v[2:5]
	global_load_dwordx4 v[156:159], v[56:57], off offset:1856
	global_load_dwordx4 v[228:231], v[58:59], off offset:1856
	s_waitcnt vmcnt(30)
	v_mfma_f32_16x16x32_bf16 v[2:5], v[168:171], v[232:235], v[2:5]
	global_load_dwordx4 v[168:171], v[56:57], off offset:1920
	global_load_dwordx4 v[232:235], v[58:59], off offset:1920
	s_waitcnt vmcnt(30)
	v_mfma_f32_16x16x32_bf16 v[2:5], v[172:175], v[236:239], v[2:5]
	global_load_dwordx4 v[172:175], v[56:57], off offset:1984
	global_load_dwordx4 v[236:239], v[58:59], off offset:1984
	s_waitcnt vmcnt(30)
	v_mfma_f32_16x16x32_bf16 v[2:5], v[24:27], v[176:179], v[2:5]
	s_waitcnt vmcnt(28)
	v_mfma_f32_16x16x32_bf16 v[2:5], v[28:31], v[180:183], v[2:5]
	s_waitcnt vmcnt(26)
	v_mfma_f32_16x16x32_bf16 v[2:5], v[32:35], v[184:187], v[2:5]
	s_waitcnt vmcnt(24)
	v_mfma_f32_16x16x32_bf16 v[2:5], v[36:39], v[188:191], v[2:5]
	s_waitcnt vmcnt(22)
	v_mfma_f32_16x16x32_bf16 v[2:5], v[40:43], v[192:195], v[2:5]
	s_waitcnt vmcnt(20)
	v_mfma_f32_16x16x32_bf16 v[2:5], v[44:47], v[196:199], v[2:5]
	s_waitcnt vmcnt(18)
	v_mfma_f32_16x16x32_bf16 v[2:5], v[48:51], v[200:203], v[2:5]
	s_waitcnt vmcnt(16)
	v_mfma_f32_16x16x32_bf16 v[2:5], v[52:55], v[204:207], v[2:5]
	s_waitcnt vmcnt(14)
	v_mfma_f32_16x16x32_bf16 v[2:5], v[132:135], v[208:211], v[2:5]
	s_waitcnt vmcnt(12)
	v_mfma_f32_16x16x32_bf16 v[2:5], v[136:139], v[212:215], v[2:5]
	s_waitcnt vmcnt(10)
	v_mfma_f32_16x16x32_bf16 v[2:5], v[140:143], v[216:219], v[2:5]
	s_waitcnt vmcnt(8)
	v_mfma_f32_16x16x32_bf16 v[2:5], v[148:151], v[220:223], v[2:5]
	s_waitcnt vmcnt(6)
	v_mfma_f32_16x16x32_bf16 v[2:5], v[152:155], v[224:227], v[2:5]
	s_waitcnt vmcnt(4)
	v_mfma_f32_16x16x32_bf16 v[2:5], v[156:159], v[228:231], v[2:5]
	s_waitcnt vmcnt(2)
	v_mfma_f32_16x16x32_bf16 v[2:5], v[168:171], v[232:235], v[2:5]
	s_waitcnt vmcnt(0)
	v_mfma_f32_16x16x32_bf16 v[2:5], v[172:175], v[236:239], v[2:5]
	s_movk_i32 s4, 0x800
	s_nop 1
	v_lshl_or_b32 v16, s8, 4, v18
	v_ashrrev_i32_e32 v17, 31, v16
	s_add_i32 s8, s8, s25
	s_nop 3
	v_cvt_pk_bf16_f32 v2, v2, v3
	v_cvt_pk_bf16_f32 v3, v4, v5
	v_lshl_add_u64 v[4:5], v[16:17], 1, v[8:9]
	s_cmpk_gt_i32 s8, 0x7f
	v_add_u32_e32 v12, s3, v12
	global_store_dwordx2 v[4:5], v[2:3], off
	s_cbranch_scc0 .LBB0_1109

.Lsks_go_c:
	v_lshrrev_b32_e32 v2, 2, v146
	v_mov_b32_e32 v7, 0
	v_and_b32_e32 v20, 12, v2
	v_lshl_or_b32 v2, s22, 4, v1
	v_mov_b32_e32 v3, v7
	v_add_u32_e32 v6, 0x4000, v2
	v_lshlrev_b64 v[4:5], 12, v[2:3]
	v_lshl_add_u64 v[8:9], s[8:9], 0, v[4:5]
	v_lshlrev_b64 v[4:5], 12, v[6:7]
	v_and_b32_e32 v6, 48, v0
	v_lshlrev_b64 v[2:3], 11, v[2:3]
	v_or_b32_e32 v2, v2, v6
	v_lshl_add_u64 v[10:11], s[6:7], 0, v[4:5]
	v_lshl_add_u64 v[12:13], s[30:31], 0, v[6:7]
	v_lshl_or_b32 v14, s24, 4, v1
	s_lshl_b32 s3, s25, 4
	v_lshl_add_u64 v[16:17], s[30:31], 0, v[2:3]
	s_mov_b32 s6, s24

.LBB0_3207:
	v_add_co_u32_e32 v58, vcc, 0x1080000, v18
	s_nop 1
	v_addc_co_u32_e32 v59, vcc, 0, v19, vcc
	v_add_co_u32_e32 v60, vcc, 0x26e13000, v16
	s_nop 1
	v_addc_co_u32_e32 v61, vcc, 0, v17, vcc
	global_load_dwordx4 v[26:29], v[58:59], off
	global_load_dwordx4 v[94:97], v[60:61], off
	global_load_dwordx4 v[30:33], v[58:59], off offset:64
	global_load_dwordx4 v[98:101], v[60:61], off offset:64
	global_load_dwordx4 v[34:37], v[58:59], off offset:128
	global_load_dwordx4 v[102:105], v[60:61], off offset:128
	global_load_dwordx4 v[38:41], v[58:59], off offset:192
	global_load_dwordx4 v[106:109], v[60:61], off offset:192
	global_load_dwordx4 v[42:45], v[58:59], off offset:256
	global_load_dwordx4 v[110:113], v[60:61], off offset:256
	global_load_dwordx4 v[46:49], v[58:59], off offset:320
	global_load_dwordx4 v[114:117], v[60:61], off offset:320
	global_load_dwordx4 v[50:53], v[58:59], off offset:384
	global_load_dwordx4 v[118:121], v[60:61], off offset:384
	global_load_dwordx4 v[54:57], v[58:59], off offset:448
	global_load_dwordx4 v[122:125], v[60:61], off offset:448
	global_load_dwordx4 v[62:65], v[58:59], off offset:512
	global_load_dwordx4 v[126:129], v[60:61], off offset:512
	global_load_dwordx4 v[66:69], v[58:59], off offset:576
	global_load_dwordx4 v[130:133], v[60:61], off offset:576
	global_load_dwordx4 v[70:73], v[58:59], off offset:640
	global_load_dwordx4 v[134:137], v[60:61], off offset:640
	global_load_dwordx4 v[74:77], v[58:59], off offset:704
	global_load_dwordx4 v[138:141], v[60:61], off offset:704
	global_load_dwordx4 v[78:81], v[58:59], off offset:768
	global_load_dwordx4 v[142:145], v[60:61], off offset:768
	global_load_dwordx4 v[82:85], v[58:59], off offset:832
	global_load_dwordx4 v[148:151], v[60:61], off offset:832
	global_load_dwordx4 v[86:89], v[58:59], off offset:896
	global_load_dwordx4 v[152:155], v[60:61], off offset:896
	global_load_dwordx4 v[90:93], v[58:59], off offset:960
	global_load_dwordx4 v[156:159], v[60:61], off offset:960
	s_waitcnt vmcnt(30)
	v_mfma_f32_16x16x32_bf16 v[2:5], v[26:29], v[94:97], v[2:5]
	global_load_dwordx4 v[26:29], v[58:59], off offset:1024
	global_load_dwordx4 v[94:97], v[60:61], off offset:1024
	s_waitcnt vmcnt(30)
	v_mfma_f32_16x16x32_bf16 v[2:5], v[30:33], v[98:101], v[2:5]
	global_load_dwordx4 v[30:33], v[58:59], off offset:1088
	global_load_dwordx4 v[98:101], v[60:61], off offset:1088
	s_waitcnt vmcnt(30)
	v_mfma_f32_16x16x32_bf16 v[2:5], v[34:37], v[102:105], v[2:5]
	global_load_dwordx4 v[34:37], v[58:59], off offset:1152
	global_load_dwordx4 v[102:105], v[60:61], off offset:1152
	s_waitcnt vmcnt(30)
	v_mfma_f32_16x16x32_bf16 v[2:5], v[38:41], v[106:109], v[2:5]
	global_load_dwordx4 v[38:41], v[58:59], off offset:1216
	global_load_dwordx4 v[106:109], v[60:61], off offset:1216
	s_waitcnt vmcnt(30)
	v_mfma_f32_16x16x32_bf16 v[2:5], v[42:45], v[110:113], v[2:5]
	global_load_dwordx4 v[42:45], v[58:59], off offset:1280
	global_load_dwordx4 v[110:113], v[60:61], off offset:1280
	s_waitcnt vmcnt(30)
	v_mfma_f32_16x16x32_bf16 v[2:5], v[46:49], v[114:117], v[2:5]
	global_load_dwordx4 v[46:49], v[58:59], off offset:1344
	global_load_dwordx4 v[114:117], v[60:61], off offset:1344
	s_waitcnt vmcnt(30)
	v_mfma_f32_16x16x32_bf16 v[2:5], v[50:53], v[118:121], v[2:5]
	global_load_dwordx4 v[50:53], v[58:59], off offset:1408
	global_load_dwordx4 v[118:121], v[60:61], off offset:1408
	s_waitcnt vmcnt(30)
	v_mfma_f32_16x16x32_bf16 v[2:5], v[54:57], v[122:125], v[2:5]
	global_load_dwordx4 v[54:57], v[58:59], off offset:1472
	global_load_dwordx4 v[122:125], v[60:61], off offset:1472
	s_waitcnt vmcnt(30)
	v_mfma_f32_16x16x32_bf16 v[2:5], v[62:65], v[126:129], v[2:5]
	global_load_dwordx4 v[62:65], v[58:59], off offset:1536
	global_load_dwordx4 v[126:129], v[60:61], off offset:1536
	s_waitcnt vmcnt(30)
	v_mfma_f32_16x16x32_bf16 v[2:5], v[66:69], v[130:133], v[2:5]
	global_load_dwordx4 v[66:69], v[58:59], off offset:1600
	global_load_dwordx4 v[130:133], v[60:61], off offset:1600
	s_waitcnt vmcnt(30)
	v_mfma_f32_16x16x32_bf16 v[2:5], v[70:73], v[134:137], v[2:5]
	global_load_dwordx4 v[70:73], v[58:59], off offset:1664
	global_load_dwordx4 v[134:137], v[60:61], off offset:1664
	s_waitcnt vmcnt(30)
	v_mfma_f32_16x16x32_bf16 v[2:5], v[74:77], v[138:141], v[2:5]
	global_load_dwordx4 v[74:77], v[58:59], off offset:1728
	global_load_dwordx4 v[138:141], v[60:61], off offset:1728
	s_waitcnt vmcnt(30)
	v_mfma_f32_16x16x32_bf16 v[2:5], v[78:81], v[142:145], v[2:5]
	global_load_dwordx4 v[78:81], v[58:59], off offset:1792
	global_load_dwordx4 v[142:145], v[60:61], off offset:1792
	s_waitcnt vmcnt(30)
	v_mfma_f32_16x16x32_bf16 v[2:5], v[82:85], v[148:151], v[2:5]
	global_load_dwordx4 v[82:85], v[58:59], off offset:1856
	global_load_dwordx4 v[148:151], v[60:61], off offset:1856
	s_waitcnt vmcnt(30)
	v_mfma_f32_16x16x32_bf16 v[2:5], v[86:89], v[152:155], v[2:5]
	global_load_dwordx4 v[86:89], v[58:59], off offset:1920
	global_load_dwordx4 v[152:155], v[60:61], off offset:1920
	s_waitcnt vmcnt(30)
	v_mfma_f32_16x16x32_bf16 v[2:5], v[90:93], v[156:159], v[2:5]
	global_load_dwordx4 v[90:93], v[58:59], off offset:1984
	global_load_dwordx4 v[156:159], v[60:61], off offset:1984
	s_waitcnt vmcnt(30)
	v_mfma_f32_16x16x32_bf16 v[2:5], v[26:29], v[94:97], v[2:5]
	s_waitcnt vmcnt(28)
	v_mfma_f32_16x16x32_bf16 v[2:5], v[30:33], v[98:101], v[2:5]
	s_waitcnt vmcnt(26)
	v_mfma_f32_16x16x32_bf16 v[2:5], v[34:37], v[102:105], v[2:5]
	s_waitcnt vmcnt(24)
	v_mfma_f32_16x16x32_bf16 v[2:5], v[38:41], v[106:109], v[2:5]
	s_waitcnt vmcnt(22)
	v_mfma_f32_16x16x32_bf16 v[2:5], v[42:45], v[110:113], v[2:5]
	s_waitcnt vmcnt(20)
	v_mfma_f32_16x16x32_bf16 v[2:5], v[46:49], v[114:117], v[2:5]
	s_waitcnt vmcnt(18)
	v_mfma_f32_16x16x32_bf16 v[2:5], v[50:53], v[118:121], v[2:5]
	s_waitcnt vmcnt(16)
	v_mfma_f32_16x16x32_bf16 v[2:5], v[54:57], v[122:125], v[2:5]
	s_waitcnt vmcnt(14)
	v_mfma_f32_16x16x32_bf16 v[2:5], v[62:65], v[126:129], v[2:5]
	s_waitcnt vmcnt(12)
	v_mfma_f32_16x16x32_bf16 v[2:5], v[66:69], v[130:133], v[2:5]
	s_waitcnt vmcnt(10)
	v_mfma_f32_16x16x32_bf16 v[2:5], v[70:73], v[134:137], v[2:5]
	s_waitcnt vmcnt(8)
	v_mfma_f32_16x16x32_bf16 v[2:5], v[74:77], v[138:141], v[2:5]
	s_waitcnt vmcnt(6)
	v_mfma_f32_16x16x32_bf16 v[2:5], v[78:81], v[142:145], v[2:5]
	s_waitcnt vmcnt(4)
	v_mfma_f32_16x16x32_bf16 v[2:5], v[82:85], v[148:151], v[2:5]
	s_waitcnt vmcnt(2)
	v_mfma_f32_16x16x32_bf16 v[2:5], v[86:89], v[152:155], v[2:5]
	s_waitcnt vmcnt(0)
	v_mfma_f32_16x16x32_bf16 v[2:5], v[90:93], v[156:159], v[2:5]
	s_movk_i32 s0, 0x800
	s_nop 1
	v_lshl_or_b32 v18, s6, 4, v20
	v_ashrrev_i32_e32 v19, 31, v18
	v_lshlrev_b64 v[18:19], 2, v[18:19]
	v_lshl_add_u64 v[22:23], v[8:9], 0, v[18:19]
	global_load_dwordx4 v[22:25], v[22:23], off
	s_add_i32 s6, s6, s25
	s_cmp_gt_i32 s6, 63
	v_lshl_add_u64 v[18:19], v[10:11], 0, v[18:19]
	v_add_u32_e32 v14, s3, v14
	s_waitcnt vmcnt(0)
	v_pk_add_f32 v[4:5], v[4:5], v[24:25]
	v_pk_add_f32 v[2:3], v[2:3], v[22:23]
	global_store_dwordx4 v[18:19], v[2:5], off
	s_cbranch_scc0 .LBB0_3206

.Lsks_go_d:
	v_lshrrev_b32_e32 v2, 2, v146
	v_and_b32_e32 v18, 12, v2
	v_lshl_or_b32 v2, s22, 4, v1
	v_mov_b32_e32 v7, 0
	v_add_u32_e32 v6, 0x4000, v2
	v_mov_b32_e32 v3, v7
	v_lshlrev_b64 v[4:5], 12, v[6:7]
	v_and_b32_e32 v6, 48, v0
	v_lshlrev_b64 v[2:3], 11, v[2:3]
	v_or_b32_e32 v2, v2, v6
	v_lshl_add_u64 v[8:9], s[6:7], 0, v[4:5]
	v_lshl_add_u64 v[10:11], s[30:31], 0, v[6:7]
	v_lshl_or_b32 v12, s24, 4, v1
	s_lshl_b32 s3, s25, 4
	v_lshl_add_u64 v[14:15], s[30:31], 0, v[2:3]
	s_mov_b32 s6, s24

.LBB0_3335:
	v_add_co_u32_e32 v56, vcc, 0x1680000, v16
	s_nop 1
	v_addc_co_u32_e32 v57, vcc, 0, v17, vcc
	v_add_co_u32_e32 v58, vcc, 0xdc51000, v14
	s_nop 1
	v_addc_co_u32_e32 v59, vcc, 0, v15, vcc
	global_load_dwordx4 v[24:27], v[56:57], off
	global_load_dwordx4 v[92:95], v[58:59], off
	global_load_dwordx4 v[28:31], v[56:57], off offset:64
	global_load_dwordx4 v[96:99], v[58:59], off offset:64
	global_load_dwordx4 v[32:35], v[56:57], off offset:128
	global_load_dwordx4 v[100:103], v[58:59], off offset:128
	global_load_dwordx4 v[36:39], v[56:57], off offset:192
	global_load_dwordx4 v[104:107], v[58:59], off offset:192
	global_load_dwordx4 v[40:43], v[56:57], off offset:256
	global_load_dwordx4 v[108:111], v[58:59], off offset:256
	global_load_dwordx4 v[44:47], v[56:57], off offset:320
	global_load_dwordx4 v[112:115], v[58:59], off offset:320
	global_load_dwordx4 v[48:51], v[56:57], off offset:384
	global_load_dwordx4 v[116:119], v[58:59], off offset:384
	global_load_dwordx4 v[52:55], v[56:57], off offset:448
	global_load_dwordx4 v[120:123], v[58:59], off offset:448
	global_load_dwordx4 v[60:63], v[56:57], off offset:512
	global_load_dwordx4 v[124:127], v[58:59], off offset:512
	global_load_dwordx4 v[64:67], v[56:57], off offset:576
	global_load_dwordx4 v[128:131], v[58:59], off offset:576
	global_load_dwordx4 v[68:71], v[56:57], off offset:640
	global_load_dwordx4 v[132:135], v[58:59], off offset:640
	global_load_dwordx4 v[72:75], v[56:57], off offset:704
	global_load_dwordx4 v[136:139], v[58:59], off offset:704
	global_load_dwordx4 v[76:79], v[56:57], off offset:768
	global_load_dwordx4 v[140:143], v[58:59], off offset:768
	global_load_dwordx4 v[80:83], v[56:57], off offset:832
	global_load_dwordx4 v[148:151], v[58:59], off offset:832
	global_load_dwordx4 v[84:87], v[56:57], off offset:896
	global_load_dwordx4 v[152:155], v[58:59], off offset:896
	global_load_dwordx4 v[88:91], v[56:57], off offset:960
	global_load_dwordx4 v[156:159], v[58:59], off offset:960
	s_waitcnt vmcnt(30)
	v_mfma_f32_16x16x32_bf16 v[2:5], v[24:27], v[92:95], v[2:5]
	global_load_dwordx4 v[24:27], v[56:57], off offset:1024
	global_load_dwordx4 v[92:95], v[58:59], off offset:1024
	s_waitcnt vmcnt(30)
	v_mfma_f32_16x16x32_bf16 v[2:5], v[28:31], v[96:99], v[2:5]
	global_load_dwordx4 v[28:31], v[56:57], off offset:1088
	global_load_dwordx4 v[96:99], v[58:59], off offset:1088
	s_waitcnt vmcnt(30)
	v_mfma_f32_16x16x32_bf16 v[2:5], v[32:35], v[100:103], v[2:5]
	global_load_dwordx4 v[32:35], v[56:57], off offset:1152
	global_load_dwordx4 v[100:103], v[58:59], off offset:1152
	s_waitcnt vmcnt(30)
	v_mfma_f32_16x16x32_bf16 v[2:5], v[36:39], v[104:107], v[2:5]
	global_load_dwordx4 v[36:39], v[56:57], off offset:1216
	global_load_dwordx4 v[104:107], v[58:59], off offset:1216
	s_waitcnt vmcnt(30)
	v_mfma_f32_16x16x32_bf16 v[2:5], v[40:43], v[108:111], v[2:5]
	global_load_dwordx4 v[40:43], v[56:57], off offset:1280
	global_load_dwordx4 v[108:111], v[58:59], off offset:1280
	s_waitcnt vmcnt(30)
	v_mfma_f32_16x16x32_bf16 v[2:5], v[44:47], v[112:115], v[2:5]
	global_load_dwordx4 v[44:47], v[56:57], off offset:1344
	global_load_dwordx4 v[112:115], v[58:59], off offset:1344
	s_waitcnt vmcnt(30)
	v_mfma_f32_16x16x32_bf16 v[2:5], v[48:51], v[116:119], v[2:5]
	global_load_dwordx4 v[48:51], v[56:57], off offset:1408
	global_load_dwordx4 v[116:119], v[58:59], off offset:1408
	s_waitcnt vmcnt(30)
	v_mfma_f32_16x16x32_bf16 v[2:5], v[52:55], v[120:123], v[2:5]
	global_load_dwordx4 v[52:55], v[56:57], off offset:1472
	global_load_dwordx4 v[120:123], v[58:59], off offset:1472
	s_waitcnt vmcnt(30)
	v_mfma_f32_16x16x32_bf16 v[2:5], v[60:63], v[124:127], v[2:5]
	global_load_dwordx4 v[60:63], v[56:57], off offset:1536
	global_load_dwordx4 v[124:127], v[58:59], off offset:1536
	s_waitcnt vmcnt(30)
	v_mfma_f32_16x16x32_bf16 v[2:5], v[64:67], v[128:131], v[2:5]
	global_load_dwordx4 v[64:67], v[56:57], off offset:1600
	global_load_dwordx4 v[128:131], v[58:59], off offset:1600
	s_waitcnt vmcnt(30)
	v_mfma_f32_16x16x32_bf16 v[2:5], v[68:71], v[132:135], v[2:5]
	global_load_dwordx4 v[68:71], v[56:57], off offset:1664
	global_load_dwordx4 v[132:135], v[58:59], off offset:1664
	s_waitcnt vmcnt(30)
	v_mfma_f32_16x16x32_bf16 v[2:5], v[72:75], v[136:139], v[2:5]
	global_load_dwordx4 v[72:75], v[56:57], off offset:1728
	global_load_dwordx4 v[136:139], v[58:59], off offset:1728
	s_waitcnt vmcnt(30)
	v_mfma_f32_16x16x32_bf16 v[2:5], v[76:79], v[140:143], v[2:5]
	global_load_dwordx4 v[76:79], v[56:57], off offset:1792
	global_load_dwordx4 v[140:143], v[58:59], off offset:1792
	s_waitcnt vmcnt(30)
	v_mfma_f32_16x16x32_bf16 v[2:5], v[80:83], v[148:151], v[2:5]
	global_load_dwordx4 v[80:83], v[56:57], off offset:1856
	global_load_dwordx4 v[148:151], v[58:59], off offset:1856
	s_waitcnt vmcnt(30)
	v_mfma_f32_16x16x32_bf16 v[2:5], v[84:87], v[152:155], v[2:5]
	global_load_dwordx4 v[84:87], v[56:57], off offset:1920
	global_load_dwordx4 v[152:155], v[58:59], off offset:1920
	s_waitcnt vmcnt(30)
	v_mfma_f32_16x16x32_bf16 v[2:5], v[88:91], v[156:159], v[2:5]
	global_load_dwordx4 v[88:91], v[56:57], off offset:1984
	global_load_dwordx4 v[156:159], v[58:59], off offset:1984
	s_waitcnt vmcnt(30)
	v_mfma_f32_16x16x32_bf16 v[2:5], v[24:27], v[92:95], v[2:5]
	s_waitcnt vmcnt(28)
	v_mfma_f32_16x16x32_bf16 v[2:5], v[28:31], v[96:99], v[2:5]
	s_waitcnt vmcnt(26)
	v_mfma_f32_16x16x32_bf16 v[2:5], v[32:35], v[100:103], v[2:5]
	s_waitcnt vmcnt(24)
	v_mfma_f32_16x16x32_bf16 v[2:5], v[36:39], v[104:107], v[2:5]
	s_waitcnt vmcnt(22)
	v_mfma_f32_16x16x32_bf16 v[2:5], v[40:43], v[108:111], v[2:5]
	s_waitcnt vmcnt(20)
	v_mfma_f32_16x16x32_bf16 v[2:5], v[44:47], v[112:115], v[2:5]
	s_waitcnt vmcnt(18)
	v_mfma_f32_16x16x32_bf16 v[2:5], v[48:51], v[116:119], v[2:5]
	s_waitcnt vmcnt(16)
	v_mfma_f32_16x16x32_bf16 v[2:5], v[52:55], v[120:123], v[2:5]
	s_waitcnt vmcnt(14)
	v_mfma_f32_16x16x32_bf16 v[2:5], v[60:63], v[124:127], v[2:5]
	s_waitcnt vmcnt(12)
	v_mfma_f32_16x16x32_bf16 v[2:5], v[64:67], v[128:131], v[2:5]
	s_waitcnt vmcnt(10)
	v_mfma_f32_16x16x32_bf16 v[2:5], v[68:71], v[132:135], v[2:5]
	s_waitcnt vmcnt(8)
	v_mfma_f32_16x16x32_bf16 v[2:5], v[72:75], v[136:139], v[2:5]
	s_waitcnt vmcnt(6)
	v_mfma_f32_16x16x32_bf16 v[2:5], v[76:79], v[140:143], v[2:5]
	s_waitcnt vmcnt(4)
	v_mfma_f32_16x16x32_bf16 v[2:5], v[80:83], v[148:151], v[2:5]
	s_waitcnt vmcnt(2)
	v_mfma_f32_16x16x32_bf16 v[2:5], v[84:87], v[152:155], v[2:5]
	s_waitcnt vmcnt(0)
	v_mfma_f32_16x16x32_bf16 v[2:5], v[88:91], v[156:159], v[2:5]
	s_movk_i32 s0, 0x800
	s_nop 1
	v_lshl_or_b32 v16, s6, 4, v18
	v_ashrrev_i32_e32 v17, 31, v16
	s_add_i32 s6, s6, s25
	s_nop 3
	v_cvt_pk_bf16_f32 v2, v2, v3
	v_cvt_pk_bf16_f32 v3, v4, v5
	v_lshl_add_u64 v[4:5], v[16:17], 1, v[8:9]
	s_cmpk_gt_i32 s6, 0x7f
	v_add_u32_e32 v12, s3, v12
	global_store_dwordx2 v[4:5], v[2:3], off
	s_cbranch_scc0 .LBB0_3334
